# tile heads: row-group size is the shape constant 8 (nM=128, WGM=8) so the next-tile split is a shift/mask instead of a float-reciprocal division chain; plus zeroing interleave; layout kept
# speedup vs baseline: 1.0047x; 1.0019x over previous
.Lzskip_gin:
	v_mov_b64_e32 v[18:19], 0
	v_mov_b64_e32 v[20:21], 0
	v_mov_b64_e32 v[22:23], 0
	v_mov_b64_e32 v[24:25], 0
	v_mov_b64_e32 v[26:27], 0
	v_mov_b64_e32 v[28:29], 0
	v_mov_b64_e32 v[30:31], 0
	v_mov_b64_e32 v[32:33], 0
	v_mov_b64_e32 v[34:35], 0
	v_mov_b64_e32 v[36:37], 0
	v_mov_b64_e32 v[38:39], 0
	v_mov_b64_e32 v[40:41], 0
	v_mov_b64_e32 v[42:43], 0
	v_mov_b64_e32 v[44:45], 0
	v_mov_b64_e32 v[46:47], 0
	v_mov_b64_e32 v[48:49], 0
	v_mov_b64_e32 v[50:51], 0
	v_mov_b64_e32 v[52:53], 0
	v_mov_b64_e32 v[54:55], 0
	v_mov_b64_e32 v[56:57], 0
	v_mov_b64_e32 v[58:59], 0
	v_mov_b64_e32 v[60:61], 0
	s_branch .LBB0_74
	s_nop 0
	s_nop 0
	s_nop 0
	s_nop 0
	s_nop 0
	s_nop 0
	s_nop 0
	s_nop 0
	s_nop 0
	s_nop 0
	s_nop 0
	s_nop 0
	s_nop 0
	s_nop 0
	s_nop 0
	s_nop 0
	s_nop 0
	s_nop 0
	s_nop 0
	s_nop 0
	s_nop 0

.LBB0_72:
	s_add_i32 s81, s81, 1
	v_mov_b64_e32 v[4:5], 0
	s_mul_i32 s2, s81, s48
	v_mov_b64_e32 v[6:7], 0
	s_mul_hi_u32 s6, s81, s12
	v_mov_b64_e32 v[8:9], 0
	s_add_i32 s6, s6, s2
	v_mov_b64_e32 v[10:11], 0
	s_mul_i32 s2, s81, s12
	v_mov_b64_e32 v[12:13], 0
	s_add_u32 s76, s2, s28
	v_mov_b64_e32 v[14:15], 0
	s_addc_u32 s77, s6, s17
	v_mov_b64_e32 v[16:17], 0
	v_mov_b64_e32 v[2:3], 0x600
	v_cmp_lt_i64_e64 s[38:39], s[76:77], v[2:3]
	v_mov_b64_e32 v[2:3], 0x5ff
	v_cmp_gt_i64_e32 vcc, s[76:77], v[2:3]
	s_cbranch_vccnz .Lzskip_gin
	s_ashr_i32 s2, s76, 31
	v_mov_b64_e32 v[18:19], 0
	s_lshr_b32 s2, s2, 29
	v_mov_b64_e32 v[20:21], 0
	s_add_i32 s2, s76, s2
	v_mov_b64_e32 v[22:23], 0
	s_ashr_i32 s6, s2, 3
	v_mov_b64_e32 v[24:25], 0
	s_and_b32 s2, s2, -8
	v_mov_b64_e32 v[26:27], 0
	s_sub_i32 s2, s76, s2
	v_mov_b64_e32 v[28:29], 0
	s_cmp_lt_i32 s2, 0
	v_mov_b64_e32 v[30:31], 0
	s_cselect_b32 s50, s72, 0xc0
	v_mov_b64_e32 v[32:33], 0
	s_mul_i32 s2, s2, s50
	v_mov_b64_e32 v[34:35], 0
	s_add_i32 s2, s2, s6
	v_mov_b64_e32 v[36:37], 0
	s_mul_hi_i32 s6, s2, 0x2aaaaaab
	v_mov_b64_e32 v[38:39], 0
	s_lshr_b32 s50, s6, 31
	v_mov_b64_e32 v[40:41], 0
	s_ashr_i32 s6, s6, 4
	v_mov_b64_e32 v[42:43], 0
	s_add_i32 s6, s6, s50
	v_mov_b64_e32 v[44:45], 0
	s_lshl_b32 s51, s6, 3
	v_mov_b64_e32 v[46:47], 0
	s_sub_i32 s50, 0x80, s51
	v_mov_b64_e32 v[48:49], 0
	s_min_i32 s62, s50, 8
	v_mov_b64_e32 v[50:51], 0
	s_mulk_i32 s6, 0x60
	v_mov_b64_e32 v[52:53], 0
	s_sub_i32 s2, s2, s6
	v_mov_b64_e32 v[54:55], 0
	s_lshr_b32 s50, s2, 3
	v_mov_b64_e32 v[56:57], 0
	s_and_b32 s2, s2, 7
	v_mov_b64_e32 v[58:59], 0
	s_add_i32 s62, s51, s2
	v_mov_b64_e32 v[60:61], 0
.LBB0_74:
	s_ashr_i32 s63, s62, 31
	v_mov_b64_e32 v[62:63], 0
	s_lshl_b64 s[68:69], s[62:63], 19
	v_mov_b64_e32 v[64:65], 0
	s_add_u32 s76, s36, s68
	v_mov_b64_e32 v[66:67], 0
	s_addc_u32 s77, s37, s69
	v_mov_b64_e32 v[68:69], 0
	s_and_b64 s[68:69], s[38:39], exec
	v_mov_b64_e32 v[70:71], 0
	s_cselect_b32 s2, s77, s91
	v_mov_b64_e32 v[72:73], 0
	s_cselect_b32 s6, s76, s90
	v_mov_b64_e32 v[74:75], 0
	s_ashr_i32 s51, s50, 31
	v_mov_b64_e32 v[76:77], 0
	s_lshl_b64 s[68:69], s[50:51], 19
	v_mov_b64_e32 v[78:79], 0
	s_add_u32 s78, s42, s68
	v_mov_b64_e32 v[80:81], 0
	s_addc_u32 s79, s43, s69
	v_mov_b64_e32 v[82:83], 0
	s_and_b64 s[68:69], s[38:39], exec
	v_mov_b64_e32 v[84:85], 0
	s_cselect_b32 s51, s79, s93
	v_mov_b64_e32 v[86:87], 0
	s_cselect_b32 s63, s78, s92
	v_mov_b64_e32 v[88:89], 0
	s_add_u32 s90, s90, 0x40080
	v_mov_b64_e32 v[90:91], 0
	s_addc_u32 s91, s91, 0
	v_mov_b64_e32 v[92:93], 0
	s_add_u32 s89, s92, 0x100
	v_mov_b64_e32 v[94:95], 0
	v_mov_b64_e32 v[2:3], 0
	v_mov_b64_e32 v[96:97], 0
	v_mov_b64_e32 v[98:99], 0
	v_mov_b64_e32 v[100:101], 0
	v_mov_b64_e32 v[102:103], 0
	v_mov_b64_e32 v[104:105], 0
	v_mov_b64_e32 v[106:107], 0
	v_mov_b64_e32 v[108:109], 0
	v_mov_b64_e32 v[110:111], 0
	v_mov_b64_e32 v[112:113], 0
	v_mov_b64_e32 v[114:115], 0
	v_mov_b64_e32 v[116:117], 0
	v_mov_b64_e32 v[118:119], 0
	v_mov_b64_e32 v[120:121], 0
	v_mov_b64_e32 v[122:123], 0
	v_mov_b64_e32 v[124:125], 0
	v_mov_b64_e32 v[126:127], 0
	v_mov_b64_e32 v[128:129], 0
	s_addc_u32 s96, s93, 0
	s_mov_b32 s97, -2

.Lzskip_gdn:
	v_mov_b64_e32 v[20:21], 0
	v_mov_b64_e32 v[22:23], 0
	v_mov_b64_e32 v[24:25], 0
	v_mov_b64_e32 v[26:27], 0
	v_mov_b64_e32 v[28:29], 0
	v_mov_b64_e32 v[30:31], 0
	v_mov_b64_e32 v[32:33], 0
	v_mov_b64_e32 v[34:35], 0
	v_mov_b64_e32 v[36:37], 0
	v_mov_b64_e32 v[38:39], 0
	v_mov_b64_e32 v[40:41], 0
	v_mov_b64_e32 v[42:43], 0
	v_mov_b64_e32 v[44:45], 0
	v_mov_b64_e32 v[46:47], 0
	s_branch .LBB0_183
	s_nop 0
	s_nop 0
	s_nop 0
	s_nop 0
	s_nop 0
	s_nop 0
	s_nop 0
	s_nop 0
	s_nop 0
	s_nop 0
	s_nop 0
	s_nop 0
	s_nop 0

.LBB0_182:
	s_ashr_i32 s2, s2, 3
	v_mov_b64_e32 v[20:21], 0
	s_add_i32 s2, s88, s2
	v_mov_b64_e32 v[22:23], 0
	s_ashr_i32 s6, s2, 31
	v_mov_b64_e32 v[24:25], 0
	s_lshr_b32 s6, s6, 27
	v_mov_b64_e32 v[26:27], 0
	s_add_i32 s6, s2, s6
	v_mov_b64_e32 v[28:29], 0
	s_ashr_i32 s38, s6, 5
	v_mov_b64_e32 v[30:31], 0
	s_lshl_b32 s38, s38, 3
	v_mov_b64_e32 v[32:33], 0
	s_sub_i32 s39, 0x80, s38
	v_mov_b64_e32 v[34:35], 0
	s_min_i32 s39, s39, 8
	v_mov_b64_e32 v[36:37], 0
	s_andn2_b32 s6, s6, 31
	v_mov_b64_e32 v[38:39], 0
	s_sub_i32 s6, s2, s6
	v_mov_b64_e32 v[40:41], 0
	s_lshr_b32 s2, s6, 3
	v_mov_b64_e32 v[42:43], 0
	s_and_b32 s6, s6, 7
	v_mov_b64_e32 v[44:45], 0
	s_add_i32 s6, s38, s6
	v_mov_b64_e32 v[46:47], 0
.LBB0_183:
	v_cndmask_b32_e64 v2, 0, 1, s[40:41]
	v_mov_b64_e32 v[48:49], 0
	v_cmp_ne_u32_e64 s[38:39], 1, v2
	v_mov_b64_e32 v[50:51], 0
	s_andn2_b64 vcc, exec, s[40:41]
	v_mov_b64_e32 v[52:53], 0
	s_mov_b64 s[88:89], s[94:95]
	v_mov_b64_e32 v[54:55], 0
	s_cbranch_vccnz .LBB0_185
	s_mul_i32 s41, s17, s6
	s_mul_hi_i32 s40, s17, s6
	s_add_u32 s88, s50, s41
	s_addc_u32 s89, s51, s40

.LBB0_187:
	s_add_u32 s40, s94, 0x80
	v_mov_b64_e32 v[56:57], 0
	s_addc_u32 s41, s95, 0
	v_mov_b64_e32 v[58:59], 0
	s_add_u32 s94, s92, 0x100
	v_mov_b64_e32 v[60:61], 0
	v_mov_b64_e32 v[2:3], 0
	v_mov_b64_e32 v[62:63], 0
	v_mov_b64_e32 v[64:65], 0
	v_mov_b64_e32 v[66:67], 0
	v_mov_b64_e32 v[68:69], 0
	v_mov_b64_e32 v[70:71], 0
	v_mov_b64_e32 v[72:73], 0
	v_mov_b64_e32 v[74:75], 0
	v_mov_b64_e32 v[76:77], 0
	v_mov_b64_e32 v[78:79], 0
	v_mov_b64_e32 v[80:81], 0
	v_mov_b64_e32 v[82:83], 0
	v_mov_b64_e32 v[84:85], 0
	v_mov_b64_e32 v[86:87], 0
	v_mov_b64_e32 v[88:89], 0
	v_mov_b64_e32 v[90:91], 0
	v_mov_b64_e32 v[92:93], 0
	v_mov_b64_e32 v[94:95], 0
	v_mov_b64_e32 v[96:97], 0
	v_mov_b64_e32 v[98:99], 0
	v_mov_b64_e32 v[100:101], 0
	v_mov_b64_e32 v[102:103], 0
	v_mov_b64_e32 v[104:105], 0
	v_mov_b64_e32 v[114:115], 0
	v_mov_b64_e32 v[116:117], 0
	v_mov_b64_e32 v[118:119], 0
	v_mov_b64_e32 v[120:121], 0
	v_mov_b64_e32 v[130:131], 0
	v_mov_b64_e32 v[132:133], 0
	v_mov_b64_e32 v[134:135], 0
	v_mov_b64_e32 v[136:137], 0
	v_mov_b64_e32 v[138:139], 0
	v_mov_b64_e32 v[140:141], 0
	v_mov_b64_e32 v[142:143], 0
	v_mov_b64_e32 v[144:145], 0
	s_addc_u32 s95, s93, 0
	s_mov_b32 s92, 0

.Lzskip_gup:
	v_mov_b64_e32 v[30:31], 0
	v_mov_b64_e32 v[32:33], 0
	v_mov_b64_e32 v[34:35], 0
	v_mov_b64_e32 v[36:37], 0
	v_mov_b64_e32 v[38:39], 0
	v_mov_b64_e32 v[40:41], 0
	v_mov_b64_e32 v[42:43], 0
	v_mov_b64_e32 v[44:45], 0
	v_mov_b64_e32 v[46:47], 0
	v_mov_b64_e32 v[48:49], 0
	v_mov_b64_e32 v[50:51], 0
	v_mov_b64_e32 v[52:53], 0
	v_mov_b64_e32 v[54:55], 0
	v_mov_b64_e32 v[56:57], 0
	v_mov_b64_e32 v[58:59], 0
	v_mov_b64_e32 v[60:61], 0
	v_mov_b64_e32 v[62:63], 0
	v_mov_b64_e32 v[64:65], 0
	v_mov_b64_e32 v[66:67], 0
	v_mov_b64_e32 v[68:69], 0
	v_mov_b64_e32 v[70:71], 0
	v_mov_b64_e32 v[72:73], 0
	v_mov_b64_e32 v[86:87], 0
	s_branch .LBB0_242
	s_nop 0
	s_nop 0
	s_nop 0
	s_nop 0
	s_nop 0
	s_nop 0
	s_nop 0
	s_nop 0
	s_nop 0
	s_nop 0
	s_nop 0
	s_nop 0
	s_nop 0
	s_nop 0
	s_nop 0
	s_nop 0
	s_nop 0
	s_nop 0
	s_nop 0
	s_nop 0

.LBB0_240:
	s_add_i32 s23, s23, 1
	v_mov_b64_e32 v[4:5], 0
	s_mul_i32 s2, s23, s21
	v_mov_b64_e32 v[6:7], 0
	s_mul_hi_u32 s6, s23, s12
	v_mov_b64_e32 v[8:9], 0
	s_add_i32 s6, s6, s2
	v_mov_b64_e32 v[10:11], 0
	s_mul_i32 s2, s23, s12
	v_mov_b64_e32 v[12:13], 0
	s_add_u32 s90, s2, s28
	v_mov_b64_e32 v[18:19], 0
	s_addc_u32 s91, s6, s22
	v_mov_b64_e32 v[20:21], 0
	v_mov_b64_e32 v[2:3], 0xb00
	v_cmp_lt_i64_e64 s[38:39], s[90:91], v[2:3]
	v_mov_b64_e32 v[2:3], 0xaff
	v_cmp_gt_i64_e32 vcc, s[90:91], v[2:3]
	s_cbranch_vccnz .Lzskip_gup
	s_ashr_i32 s2, s90, 31
	v_mov_b64_e32 v[30:31], 0
	s_lshr_b32 s2, s2, 29
	v_mov_b64_e32 v[32:33], 0
	s_add_i32 s2, s90, s2
	v_mov_b64_e32 v[34:35], 0
	s_ashr_i32 s6, s2, 3
	v_mov_b64_e32 v[36:37], 0
	s_and_b32 s2, s2, -8
	v_mov_b64_e32 v[38:39], 0
	s_sub_i32 s2, s90, s2
	v_mov_b64_e32 v[40:41], 0
	s_cmp_lt_i32 s2, 0
	v_mov_b64_e32 v[42:43], 0
	s_movk_i32 s41, 0x161
	v_mov_b64_e32 v[44:45], 0
	s_cselect_b32 s41, s41, 0x160
	v_mov_b64_e32 v[46:47], 0
	s_mul_i32 s2, s2, s41
	v_mov_b64_e32 v[48:49], 0
	s_add_i32 s2, s2, s6
	v_mov_b64_e32 v[50:51], 0
	s_mul_hi_i32 s6, s2, 0x2e8ba2e9
	v_mov_b64_e32 v[52:53], 0
	s_lshr_b32 s41, s6, 31
	v_mov_b64_e32 v[54:55], 0
	s_ashr_i32 s6, s6, 5
	v_mov_b64_e32 v[56:57], 0
	s_add_i32 s6, s6, s41
	v_mov_b64_e32 v[58:59], 0
	s_lshl_b32 s41, s6, 3
	v_mov_b64_e32 v[60:61], 0
	s_sub_i32 s48, 0x80, s41
	v_mov_b64_e32 v[62:63], 0
	s_min_i32 s48, s48, 8
	v_mov_b64_e32 v[64:65], 0
	s_mulk_i32 s6, 0xb0
	v_mov_b64_e32 v[66:67], 0
	s_sub_i32 s2, s2, s6
	v_mov_b64_e32 v[68:69], 0
	s_lshr_b32 s88, s2, 3
	v_mov_b64_e32 v[70:71], 0
	s_and_b32 s2, s2, 7
	v_mov_b64_e32 v[72:73], 0
	s_add_i32 s94, s41, s2
	v_mov_b64_e32 v[86:87], 0
.LBB0_242:
	s_ashr_i32 s95, s94, 31
	v_mov_b64_e32 v[88:89], 0
	s_lshl_b64 s[70:71], s[94:95], 19
	v_mov_b64_e32 v[90:91], 0
	s_add_u32 s90, s36, s70
	v_mov_b64_e32 v[92:93], 0
	s_addc_u32 s91, s37, s71
	v_mov_b64_e32 v[94:95], 0
	s_and_b64 s[70:71], s[38:39], exec
	v_mov_b64_e32 v[96:97], 0
	s_cselect_b32 s2, s91, s43
	v_mov_b64_e32 v[98:99], 0
	s_cselect_b32 s6, s90, s42
	v_mov_b64_e32 v[100:101], 0
	s_ashr_i32 s89, s88, 31
	v_mov_b64_e32 v[102:103], 0
	s_lshl_b64 s[70:71], s[88:89], 19
	v_mov_b64_e32 v[104:105], 0
	s_add_u32 s96, s50, s70
	v_mov_b64_e32 v[106:107], 0
	s_addc_u32 s97, s51, s71
	v_mov_b64_e32 v[108:109], 0
	s_and_b64 s[70:71], s[38:39], exec
	v_mov_b64_e32 v[110:111], 0
	s_cselect_b32 s41, s97, s93
	v_mov_b64_e32 v[112:113], 0
	s_cselect_b32 s48, s96, s92
	v_mov_b64_e32 v[114:115], 0
	s_add_u32 s42, s42, 0x40080
	v_mov_b64_e32 v[116:117], 0
	s_addc_u32 s43, s43, 0
	v_mov_b64_e32 v[118:119], 0
	s_add_u32 s77, s92, 0x100
	v_mov_b64_e32 v[120:121], 0
	v_mov_b64_e32 v[2:3], 0
	v_mov_b64_e32 v[122:123], 0
	v_mov_b64_e32 v[124:125], 0
	v_mov_b64_e32 v[126:127], 0
	v_mov_b64_e32 v[128:129], 0
	v_mov_b64_e32 v[130:131], 0
	v_mov_b64_e32 v[132:133], 0
	v_mov_b64_e32 v[134:135], 0
	v_mov_b64_e32 v[136:137], 0
	v_mov_b64_e32 v[138:139], 0
	v_mov_b64_e32 v[140:141], 0
	v_mov_b64_e32 v[142:143], 0
	v_mov_b64_e32 v[144:145], 0
	v_mov_b64_e32 v[146:147], 0
	v_mov_b64_e32 v[148:149], 0
	v_mov_b64_e32 v[150:151], 0
	v_mov_b64_e32 v[152:153], 0
	s_addc_u32 s89, s93, 0
	s_mov_b32 s95, -2
	s_waitcnt lgkmcnt(0)
